# down-projection sample rows (both layers): LDS-DMA staged K-split 32x64 tile replaces direct-from-global small_gemm_ks; same summation order
# speedup vs baseline: 1.0477x; 1.0217x over previous
; template <class F>
; __device__ __forceinline__ void small_gemm_ks(LAS unsigned char* lds, const bf16_t* A, int lda, const bf16_t* Bt, int ldb, int K, int N, int a_grp_cols, int bx, int G, int tid, const F& f) {
;     const int lane = tid & 63, w = __builtin_amdgcn_readfirstlane(tid >> 6), c = lane & 15, g = lane >> 4, kh = w >> 2, wq = w & 3, wm = wq >> 1, wn = wq & 1;
;     const int ntn = N / 64, ntiles = (MS / 32) * ntn, KH = K / 2;
;     for (int t = bx; t < ntiles; t += G) {
;         const int row0 = MP + (t / ntn) * 32 + wm * 16, n0 = (t % ntn) * 64 + wn * 32;
;         const bf16_t* ap = A + (size_t)(row0 + c) * lda + (n0 >> 8) * a_grp_cols + kh * KH + 8 * g;
;         const bf16_t* bp = Bt + (size_t)(n0 + c) * ldb + kh * KH + 8 * g;
;         f32x4 acc[2] = {(f32x4){0.f, 0.f, 0.f, 0.f}, (f32x4){0.f, 0.f, 0.f, 0.f}};
; #pragma unroll 8
;         for (int k0 = 0; k0 < KH; k0 += 32) { const bf16x8 av = *(const bf16x8*)(ap + k0);
; #pragma unroll
;             for (int nt = 0; nt < 2; ++nt) { const bf16x8 bv = *(const bf16x8*)(bp + (size_t)nt * 16 * ldb + k0); acc[nt] = __builtin_amdgcn_mfma_f32_16x16x32_bf16(av, bv, acc[nt], 0, 0, 0); } }
.LBB0_886:
	s_waitcnt lgkmcnt(0)
	s_add_u32 s0, s6, 0xc80000
	s_addc_u32 s1, s7, 0
	s_add_u32 s3, s6, 0x9900000
	s_addc_u32 s4, s7, 0
	s_add_u32 s6, s6, 0x5700000
	s_addc_u32 s7, s7, 0
	v_readfirstlane_b32 s8, v20
	s_and_b64 vcc, exec, s[88:89]
	v_and_b32_e32 v14, 15, v20
	s_cbranch_vccnz .LBB0_893
	v_readfirstlane_b32 s68, v208
	v_and_b32_e32 v86, 63, v208
	s_nop 3
	s_lshr_b32 s68, s68, 6
	v_and_b32_e32 v87, 7, v86
	v_lshrrev_b32_e32 v88, 3, v86
	s_mov_b32 s69, 5632
	v_mul_lo_u32 v90, v87, s69
	v_lshl_add_u32 v90, v88, 4, v90
	v_mov_b32_e32 v91, 0
	s_mov_b32 s69, 5632
	v_mul_lo_u32 v92, v87, s69
	v_lshl_add_u32 v92, v88, 4, v92
	v_mov_b32_e32 v93, 0
	v_and_b32_e32 v87, 15, v86
	v_lshrrev_b32_e32 v88, 4, v86
	v_lshrrev_b32_e32 v89, 3, v87
	v_lshlrev_b32_e32 v89, 10, v89
	v_lshl_add_u32 v89, v88, 7, v89
	v_and_b32_e32 v94, 7, v87
	v_lshl_add_u32 v89, v94, 4, v89
	s_lshr_b32 s70, s68, 2
	s_bfe_u32 s71, s68, 0x10001
	s_and_b32 s72, s68, 1
	s_lshl_b32 s73, s70, 12
	s_lshl_b32 s74, s71, 11
	s_add_i32 s73, s73, s74
	s_lshl_b32 s74, s70, 13
	s_lshl_b32 s75, s72, 12
	s_add_i32 s74, s74, s75
	s_add_i32 s74, s74, 0x2000
	v_add_u32_e32 v96, s73, v89
	v_add_u32_e32 v101, s74, v89
	v_add_u32_e32 v97, s73, v89
	v_add_u32_e32 v102, s74, v89
	v_add_u32_e32 v98, s73, v89
	v_add_u32_e32 v103, s74, v89
	v_add_u32_e32 v99, s73, v89
	v_add_u32_e32 v104, s74, v89
	v_add_u32_e32 v100, s73, v89
	v_add_u32_e32 v105, s74, v89
	v_add_u32_e32 v97, 24576, v97
	v_add_u32_e32 v102, 24576, v102
	v_add_u32_e32 v98, 49152, v98
	v_add_u32_e32 v103, 49152, v103
	v_add_u32_e32 v99, 73728, v99
	v_add_u32_e32 v104, 73728, v104
	v_add_u32_e32 v100, 98304, v100
	v_add_u32_e32 v105, 98304, v105
	s_lshl_b32 s75, s71, 4
	v_lshl_add_u32 v106, v88, 2, s75
	v_lshlrev_b32_e32 v106, 11, v106
	s_lshl_b32 s75, s72, 5
	v_add_u32_e32 v107, s75, v87
	v_lshl_add_u32 v106, v107, 1, v106
	v_lshlrev_b32_e32 v108, 2, v107
	v_mov_b32_e32 v107, 0
	s_and_b32 s75, s68, 3
	s_lshl_b32 s75, s75, 11
	v_lshl_add_u32 v109, v86, 4, s75
	s_lshl_b32 s76, s68, 10
	s_lshl_b32 s77, s68, 11
	s_add_i32 s77, s77, 0x2000
	s_mov_b32 s78, 0x80
	s_mov_b32 s79, 0
	s_and_b32 s80, s68, 3
	s_mov_b32 s81, s2
.Lsg_dn0_tile:
	s_lshr_b32 s82, s81, 4
	s_lshl_b32 s82, s82, 5
	s_add_i32 s82, s82, 0x4000
	s_and_b32 s83, s81, 15
	s_lshl_b32 s83, s83, 6
	s_lshl_b32 s59, s80, 3
	s_add_i32 s59, s59, s82
	s_mul_i32 s60, s59, 5632
	s_mul_hi_u32 s61, s59, 5632
	s_mul_i32 s62, s70, 2816
	s_add_u32 s60, s60, s62
	s_addc_u32 s61, s61, 0
	s_add_u32 s60, s60, s54
	s_addc_u32 s61, s61, s55
	s_add_u32 s60, s60, 0x9900000
	s_addc_u32 s61, s61, 0
	v_lshl_add_u64 v[110:111], s[60:61], 0, v[90:91]
	s_lshl_b32 s59, s80, 4
	s_add_i32 s59, s59, s83
	s_mul_i32 s60, s59, 5632
	s_mul_i32 s62, s70, 2816
	s_add_u32 s60, s60, s62
	s_add_u32 s60, s60, s54
	s_addc_u32 s61, s55, 0
	s_add_u32 s60, s60, 0xc80000
	s_addc_u32 s61, s61, 0
	v_lshl_add_u64 v[112:113], s[60:61], 0, v[92:93]
	s_add_u32 s60, s60, 45056
	s_addc_u32 s61, s61, 0
	v_lshl_add_u64 v[114:115], s[60:61], 0, v[92:93]
	s_waitcnt vmcnt(0)
	v_mov_b32_e32 v120, 0
	v_mov_b32_e32 v121, 0
	v_mov_b32_e32 v122, 0
	v_mov_b32_e32 v123, 0
	v_mov_b32_e32 v124, 0
	v_mov_b32_e32 v125, 0
	v_mov_b32_e32 v126, 0
	v_mov_b32_e32 v127, 0
	s_add_i32 m0, s76, 0
	s_nop 0
	global_load_lds_dwordx4 v[110:111], off
	v_lshl_add_u64 v[110:111], v[110:111], 0, s[78:79]
	s_add_i32 m0, s77, 0
	s_nop 0
	global_load_lds_dwordx4 v[112:113], off
	v_lshl_add_u64 v[112:113], v[112:113], 0, s[78:79]
	s_add_i32 m0, s77, 1024
	s_nop 0
	global_load_lds_dwordx4 v[114:115], off
	v_lshl_add_u64 v[114:115], v[114:115], 0, s[78:79]
	s_add_i32 m0, s76, 24576
	s_nop 0
	global_load_lds_dwordx4 v[110:111], off
	v_lshl_add_u64 v[110:111], v[110:111], 0, s[78:79]
	s_add_i32 m0, s77, 24576
	s_nop 0
	global_load_lds_dwordx4 v[112:113], off
	v_lshl_add_u64 v[112:113], v[112:113], 0, s[78:79]
	s_add_i32 m0, s77, 25600
	s_nop 0
	global_load_lds_dwordx4 v[114:115], off
	v_lshl_add_u64 v[114:115], v[114:115], 0, s[78:79]
	s_add_i32 m0, s76, 49152
	s_nop 0
	global_load_lds_dwordx4 v[110:111], off
	v_lshl_add_u64 v[110:111], v[110:111], 0, s[78:79]
	s_add_i32 m0, s77, 49152
	s_nop 0
	global_load_lds_dwordx4 v[112:113], off
	v_lshl_add_u64 v[112:113], v[112:113], 0, s[78:79]
	s_add_i32 m0, s77, 50176
	s_nop 0
	global_load_lds_dwordx4 v[114:115], off
	v_lshl_add_u64 v[114:115], v[114:115], 0, s[78:79]
	s_add_i32 m0, s76, 73728
	s_nop 0
	global_load_lds_dwordx4 v[110:111], off
	v_lshl_add_u64 v[110:111], v[110:111], 0, s[78:79]
	s_add_i32 m0, s77, 73728
	s_nop 0
	global_load_lds_dwordx4 v[112:113], off
	v_lshl_add_u64 v[112:113], v[112:113], 0, s[78:79]
	s_add_i32 m0, s77, 74752
	s_nop 0
	global_load_lds_dwordx4 v[114:115], off
	v_lshl_add_u64 v[114:115], v[114:115], 0, s[78:79]
	s_waitcnt vmcnt(9)
	s_barrier
	ds_read_b128 v[128:131], v96
	ds_read_b128 v[136:139], v101 offset:0
	ds_read_b128 v[144:147], v101 offset:2048
	ds_read_b128 v[132:135], v96 offset:512
	ds_read_b128 v[140:143], v101 offset:512
	ds_read_b128 v[148:151], v101 offset:2560
	s_add_i32 m0, s76, 98304
	s_nop 0
	global_load_lds_dwordx4 v[110:111], off
	v_lshl_add_u64 v[110:111], v[110:111], 0, s[78:79]
	s_add_i32 m0, s77, 98304
	s_nop 0
	global_load_lds_dwordx4 v[112:113], off
	v_lshl_add_u64 v[112:113], v[112:113], 0, s[78:79]
	s_add_i32 m0, s77, 99328
	s_nop 0
	global_load_lds_dwordx4 v[114:115], off
	v_lshl_add_u64 v[114:115], v[114:115], 0, s[78:79]
	s_waitcnt lgkmcnt(3)
	v_mfma_f32_16x16x32_bf16 v[120:123], v[128:131], v[136:139], v[120:123]
	v_mfma_f32_16x16x32_bf16 v[124:127], v[128:131], v[144:147], v[124:127]
	s_waitcnt lgkmcnt(0)
	v_mfma_f32_16x16x32_bf16 v[120:123], v[132:135], v[140:143], v[120:123]
	v_mfma_f32_16x16x32_bf16 v[124:127], v[132:135], v[148:151], v[124:127]
	s_waitcnt vmcnt(9)
	s_barrier
; template <class F>
; __device__ __forceinline__ void small_gemm_ks(LAS unsigned char* lds, const bf16_t* A, int lda, const bf16_t* Bt, int ldb, int K, int N, int a_grp_cols, int bx, int G, int tid, const F& f) {
;     ...
;         for (int k0 = 0; k0 < KH; k0 += 32) { const bf16x8 av = *(const bf16x8*)(ap + k0);
; #pragma unroll
;             for (int nt = 0; nt < 2; ++nt) { const bf16x8 bv = *(const bf16x8*)(bp + (size_t)nt * 16 * ldb + k0); acc[nt] = __builtin_amdgcn_mfma_f32_16x16x32_bf16(av, bv, acc[nt], 0, 0, 0); } }
	ds_read_b128 v[152:155], v97
	ds_read_b128 v[160:163], v102 offset:0
	ds_read_b128 v[168:171], v102 offset:2048
	ds_read_b128 v[156:159], v97 offset:512
	ds_read_b128 v[164:167], v102 offset:512
	ds_read_b128 v[172:175], v102 offset:2560
	s_add_i32 m0, s76, 0
	s_nop 0
	global_load_lds_dwordx4 v[110:111], off
	v_lshl_add_u64 v[110:111], v[110:111], 0, s[78:79]
	s_add_i32 m0, s77, 0
	s_nop 0
	global_load_lds_dwordx4 v[112:113], off
	v_lshl_add_u64 v[112:113], v[112:113], 0, s[78:79]
	s_add_i32 m0, s77, 1024
	s_nop 0
	global_load_lds_dwordx4 v[114:115], off
	v_lshl_add_u64 v[114:115], v[114:115], 0, s[78:79]
	s_waitcnt lgkmcnt(3)
	v_mfma_f32_16x16x32_bf16 v[120:123], v[152:155], v[160:163], v[120:123]
	v_mfma_f32_16x16x32_bf16 v[124:127], v[152:155], v[168:171], v[124:127]
	s_waitcnt lgkmcnt(0)
	v_mfma_f32_16x16x32_bf16 v[120:123], v[156:159], v[164:167], v[120:123]
	v_mfma_f32_16x16x32_bf16 v[124:127], v[156:159], v[172:175], v[124:127]
	s_waitcnt vmcnt(9)
	s_barrier
	ds_read_b128 v[128:131], v98
	ds_read_b128 v[136:139], v103 offset:0
	ds_read_b128 v[144:147], v103 offset:2048
	ds_read_b128 v[132:135], v98 offset:512
	ds_read_b128 v[140:143], v103 offset:512
	ds_read_b128 v[148:151], v103 offset:2560
	s_add_i32 m0, s76, 24576
	s_nop 0
	global_load_lds_dwordx4 v[110:111], off
	v_lshl_add_u64 v[110:111], v[110:111], 0, s[78:79]
	s_add_i32 m0, s77, 24576
	s_nop 0
	global_load_lds_dwordx4 v[112:113], off
	v_lshl_add_u64 v[112:113], v[112:113], 0, s[78:79]
	s_add_i32 m0, s77, 25600
	s_nop 0
	global_load_lds_dwordx4 v[114:115], off
	v_lshl_add_u64 v[114:115], v[114:115], 0, s[78:79]
	s_waitcnt lgkmcnt(3)
	v_mfma_f32_16x16x32_bf16 v[120:123], v[128:131], v[136:139], v[120:123]
	v_mfma_f32_16x16x32_bf16 v[124:127], v[128:131], v[144:147], v[124:127]
	s_waitcnt lgkmcnt(0)
	v_mfma_f32_16x16x32_bf16 v[120:123], v[132:135], v[140:143], v[120:123]
	v_mfma_f32_16x16x32_bf16 v[124:127], v[132:135], v[148:151], v[124:127]
	s_waitcnt vmcnt(9)
	s_barrier
	ds_read_b128 v[152:155], v99
	ds_read_b128 v[160:163], v104 offset:0
	ds_read_b128 v[168:171], v104 offset:2048
	ds_read_b128 v[156:159], v99 offset:512
	ds_read_b128 v[164:167], v104 offset:512
	ds_read_b128 v[172:175], v104 offset:2560
	s_add_i32 m0, s76, 49152
	s_nop 0
	global_load_lds_dwordx4 v[110:111], off
	v_lshl_add_u64 v[110:111], v[110:111], 0, s[78:79]
	s_add_i32 m0, s77, 49152
	s_nop 0
	global_load_lds_dwordx4 v[112:113], off
	v_lshl_add_u64 v[112:113], v[112:113], 0, s[78:79]
	s_add_i32 m0, s77, 50176
	s_nop 0
	global_load_lds_dwordx4 v[114:115], off
	v_lshl_add_u64 v[114:115], v[114:115], 0, s[78:79]
	s_waitcnt lgkmcnt(3)
	v_mfma_f32_16x16x32_bf16 v[120:123], v[152:155], v[160:163], v[120:123]
	v_mfma_f32_16x16x32_bf16 v[124:127], v[152:155], v[168:171], v[124:127]
	s_waitcnt lgkmcnt(0)
	v_mfma_f32_16x16x32_bf16 v[120:123], v[156:159], v[164:167], v[120:123]
	v_mfma_f32_16x16x32_bf16 v[124:127], v[156:159], v[172:175], v[124:127]
	s_waitcnt vmcnt(9)
	s_barrier
	ds_read_b128 v[128:131], v100
	ds_read_b128 v[136:139], v105 offset:0
	ds_read_b128 v[144:147], v105 offset:2048
	ds_read_b128 v[132:135], v100 offset:512
	ds_read_b128 v[140:143], v105 offset:512
	ds_read_b128 v[148:151], v105 offset:2560
	s_add_i32 m0, s76, 73728
	s_nop 0
	global_load_lds_dwordx4 v[110:111], off
	v_lshl_add_u64 v[110:111], v[110:111], 0, s[78:79]
	s_add_i32 m0, s77, 73728
	s_nop 0
	global_load_lds_dwordx4 v[112:113], off
	v_lshl_add_u64 v[112:113], v[112:113], 0, s[78:79]
	s_add_i32 m0, s77, 74752
	s_nop 0
	global_load_lds_dwordx4 v[114:115], off
	v_lshl_add_u64 v[114:115], v[114:115], 0, s[78:79]
	s_waitcnt lgkmcnt(3)
	v_mfma_f32_16x16x32_bf16 v[120:123], v[128:131], v[136:139], v[120:123]
	v_mfma_f32_16x16x32_bf16 v[124:127], v[128:131], v[144:147], v[124:127]
	s_waitcnt lgkmcnt(0)
	v_mfma_f32_16x16x32_bf16 v[120:123], v[132:135], v[140:143], v[120:123]
	v_mfma_f32_16x16x32_bf16 v[124:127], v[132:135], v[148:151], v[124:127]
	s_waitcnt vmcnt(9)
	s_barrier
	ds_read_b128 v[152:155], v96
	ds_read_b128 v[160:163], v101 offset:0
	ds_read_b128 v[168:171], v101 offset:2048
	ds_read_b128 v[156:159], v96 offset:512
	ds_read_b128 v[164:167], v101 offset:512
	ds_read_b128 v[172:175], v101 offset:2560
	s_add_i32 m0, s76, 98304
	s_nop 0
	global_load_lds_dwordx4 v[110:111], off
	v_lshl_add_u64 v[110:111], v[110:111], 0, s[78:79]
	s_add_i32 m0, s77, 98304
	s_nop 0
	global_load_lds_dwordx4 v[112:113], off
	v_lshl_add_u64 v[112:113], v[112:113], 0, s[78:79]
	s_add_i32 m0, s77, 99328
	s_nop 0
	global_load_lds_dwordx4 v[114:115], off
	v_lshl_add_u64 v[114:115], v[114:115], 0, s[78:79]
	s_waitcnt lgkmcnt(3)
	v_mfma_f32_16x16x32_bf16 v[120:123], v[152:155], v[160:163], v[120:123]
	v_mfma_f32_16x16x32_bf16 v[124:127], v[152:155], v[168:171], v[124:127]
	s_waitcnt lgkmcnt(0)
	v_mfma_f32_16x16x32_bf16 v[120:123], v[156:159], v[164:167], v[120:123]
	v_mfma_f32_16x16x32_bf16 v[124:127], v[156:159], v[172:175], v[124:127]
	s_waitcnt vmcnt(9)
	s_barrier
	ds_read_b128 v[128:131], v97
	ds_read_b128 v[136:139], v102 offset:0
	ds_read_b128 v[144:147], v102 offset:2048
	ds_read_b128 v[132:135], v97 offset:512
	ds_read_b128 v[140:143], v102 offset:512
	ds_read_b128 v[148:151], v102 offset:2560
	s_add_i32 m0, s76, 0
	s_nop 0
	global_load_lds_dwordx4 v[110:111], off
	v_lshl_add_u64 v[110:111], v[110:111], 0, s[78:79]
	s_add_i32 m0, s77, 0
	s_nop 0
	global_load_lds_dwordx4 v[112:113], off
	v_lshl_add_u64 v[112:113], v[112:113], 0, s[78:79]
	s_add_i32 m0, s77, 1024
	s_nop 0
	global_load_lds_dwordx4 v[114:115], off
	v_lshl_add_u64 v[114:115], v[114:115], 0, s[78:79]
	s_waitcnt lgkmcnt(3)
	v_mfma_f32_16x16x32_bf16 v[120:123], v[128:131], v[136:139], v[120:123]
	v_mfma_f32_16x16x32_bf16 v[124:127], v[128:131], v[144:147], v[124:127]
	s_waitcnt lgkmcnt(0)
	v_mfma_f32_16x16x32_bf16 v[120:123], v[132:135], v[140:143], v[120:123]
	v_mfma_f32_16x16x32_bf16 v[124:127], v[132:135], v[148:151], v[124:127]
	s_waitcnt vmcnt(9)
	s_barrier
; template <class F>
; __device__ __forceinline__ void small_gemm_ks(LAS unsigned char* lds, const bf16_t* A, int lda, const bf16_t* Bt, int ldb, int K, int N, int a_grp_cols, int bx, int G, int tid, const F& f) {
;     ...
;         for (int k0 = 0; k0 < KH; k0 += 32) { const bf16x8 av = *(const bf16x8*)(ap + k0);
; #pragma unroll
;             for (int nt = 0; nt < 2; ++nt) { const bf16x8 bv = *(const bf16x8*)(bp + (size_t)nt * 16 * ldb + k0); acc[nt] = __builtin_amdgcn_mfma_f32_16x16x32_bf16(av, bv, acc[nt], 0, 0, 0); } }
	ds_read_b128 v[152:155], v98
	ds_read_b128 v[160:163], v103 offset:0
	ds_read_b128 v[168:171], v103 offset:2048
	ds_read_b128 v[156:159], v98 offset:512
	ds_read_b128 v[164:167], v103 offset:512
	ds_read_b128 v[172:175], v103 offset:2560
	s_add_i32 m0, s76, 24576
	s_nop 0
	global_load_lds_dwordx4 v[110:111], off
	v_lshl_add_u64 v[110:111], v[110:111], 0, s[78:79]
	s_add_i32 m0, s77, 24576
	s_nop 0
	global_load_lds_dwordx4 v[112:113], off
	v_lshl_add_u64 v[112:113], v[112:113], 0, s[78:79]
	s_add_i32 m0, s77, 25600
	s_nop 0
	global_load_lds_dwordx4 v[114:115], off
	v_lshl_add_u64 v[114:115], v[114:115], 0, s[78:79]
	s_waitcnt lgkmcnt(3)
	v_mfma_f32_16x16x32_bf16 v[120:123], v[152:155], v[160:163], v[120:123]
	v_mfma_f32_16x16x32_bf16 v[124:127], v[152:155], v[168:171], v[124:127]
	s_waitcnt lgkmcnt(0)
	v_mfma_f32_16x16x32_bf16 v[120:123], v[156:159], v[164:167], v[120:123]
	v_mfma_f32_16x16x32_bf16 v[124:127], v[156:159], v[172:175], v[124:127]
	s_waitcnt vmcnt(9)
	s_barrier
	ds_read_b128 v[128:131], v99
	ds_read_b128 v[136:139], v104 offset:0
	ds_read_b128 v[144:147], v104 offset:2048
	ds_read_b128 v[132:135], v99 offset:512
	ds_read_b128 v[140:143], v104 offset:512
	ds_read_b128 v[148:151], v104 offset:2560
	s_add_i32 m0, s76, 49152
	s_nop 0
	global_load_lds_dwordx4 v[110:111], off
	v_lshl_add_u64 v[110:111], v[110:111], 0, s[78:79]
	s_add_i32 m0, s77, 49152
	s_nop 0
	global_load_lds_dwordx4 v[112:113], off
	v_lshl_add_u64 v[112:113], v[112:113], 0, s[78:79]
	s_add_i32 m0, s77, 50176
	s_nop 0
	global_load_lds_dwordx4 v[114:115], off
	v_lshl_add_u64 v[114:115], v[114:115], 0, s[78:79]
	s_waitcnt lgkmcnt(3)
	v_mfma_f32_16x16x32_bf16 v[120:123], v[128:131], v[136:139], v[120:123]
	v_mfma_f32_16x16x32_bf16 v[124:127], v[128:131], v[144:147], v[124:127]
	s_waitcnt lgkmcnt(0)
	v_mfma_f32_16x16x32_bf16 v[120:123], v[132:135], v[140:143], v[120:123]
	v_mfma_f32_16x16x32_bf16 v[124:127], v[132:135], v[148:151], v[124:127]
	s_waitcnt vmcnt(9)
	s_barrier
	ds_read_b128 v[152:155], v100
	ds_read_b128 v[160:163], v105 offset:0
	ds_read_b128 v[168:171], v105 offset:2048
	ds_read_b128 v[156:159], v100 offset:512
	ds_read_b128 v[164:167], v105 offset:512
	ds_read_b128 v[172:175], v105 offset:2560
	s_add_i32 m0, s76, 73728
	s_nop 0
	global_load_lds_dwordx4 v[110:111], off
	v_lshl_add_u64 v[110:111], v[110:111], 0, s[78:79]
	s_add_i32 m0, s77, 73728
	s_nop 0
	global_load_lds_dwordx4 v[112:113], off
	v_lshl_add_u64 v[112:113], v[112:113], 0, s[78:79]
	s_add_i32 m0, s77, 74752
	s_nop 0
	global_load_lds_dwordx4 v[114:115], off
	v_lshl_add_u64 v[114:115], v[114:115], 0, s[78:79]
	s_waitcnt lgkmcnt(3)
	v_mfma_f32_16x16x32_bf16 v[120:123], v[152:155], v[160:163], v[120:123]
	v_mfma_f32_16x16x32_bf16 v[124:127], v[152:155], v[168:171], v[124:127]
	s_waitcnt lgkmcnt(0)
	v_mfma_f32_16x16x32_bf16 v[120:123], v[156:159], v[164:167], v[120:123]
	v_mfma_f32_16x16x32_bf16 v[124:127], v[156:159], v[172:175], v[124:127]
	s_waitcnt vmcnt(9)
	s_barrier
	ds_read_b128 v[128:131], v96
	ds_read_b128 v[136:139], v101 offset:0
	ds_read_b128 v[144:147], v101 offset:2048
	ds_read_b128 v[132:135], v96 offset:512
	ds_read_b128 v[140:143], v101 offset:512
	ds_read_b128 v[148:151], v101 offset:2560
	s_add_i32 m0, s76, 98304
	s_nop 0
	global_load_lds_dwordx4 v[110:111], off
	v_lshl_add_u64 v[110:111], v[110:111], 0, s[78:79]
	s_add_i32 m0, s77, 98304
	s_nop 0
	global_load_lds_dwordx4 v[112:113], off
	v_lshl_add_u64 v[112:113], v[112:113], 0, s[78:79]
	s_add_i32 m0, s77, 99328
	s_nop 0
	global_load_lds_dwordx4 v[114:115], off
	v_lshl_add_u64 v[114:115], v[114:115], 0, s[78:79]
	s_waitcnt lgkmcnt(3)
	v_mfma_f32_16x16x32_bf16 v[120:123], v[128:131], v[136:139], v[120:123]
	v_mfma_f32_16x16x32_bf16 v[124:127], v[128:131], v[144:147], v[124:127]
	s_waitcnt lgkmcnt(0)
	v_mfma_f32_16x16x32_bf16 v[120:123], v[132:135], v[140:143], v[120:123]
	v_mfma_f32_16x16x32_bf16 v[124:127], v[132:135], v[148:151], v[124:127]
	s_waitcnt vmcnt(9)
	s_barrier
	ds_read_b128 v[152:155], v97
	ds_read_b128 v[160:163], v102 offset:0
	ds_read_b128 v[168:171], v102 offset:2048
	ds_read_b128 v[156:159], v97 offset:512
	ds_read_b128 v[164:167], v102 offset:512
	ds_read_b128 v[172:175], v102 offset:2560
	s_add_i32 m0, s76, 0
	s_nop 0
	global_load_lds_dwordx4 v[110:111], off
	v_lshl_add_u64 v[110:111], v[110:111], 0, s[78:79]
	s_add_i32 m0, s77, 0
	s_nop 0
	global_load_lds_dwordx4 v[112:113], off
	v_lshl_add_u64 v[112:113], v[112:113], 0, s[78:79]
	s_add_i32 m0, s77, 1024
	s_nop 0
	global_load_lds_dwordx4 v[114:115], off
	v_lshl_add_u64 v[114:115], v[114:115], 0, s[78:79]
	s_waitcnt lgkmcnt(3)
	v_mfma_f32_16x16x32_bf16 v[120:123], v[152:155], v[160:163], v[120:123]
	v_mfma_f32_16x16x32_bf16 v[124:127], v[152:155], v[168:171], v[124:127]
	s_waitcnt lgkmcnt(0)
	v_mfma_f32_16x16x32_bf16 v[120:123], v[156:159], v[164:167], v[120:123]
	v_mfma_f32_16x16x32_bf16 v[124:127], v[156:159], v[172:175], v[124:127]
	s_waitcnt vmcnt(9)
	s_barrier
	ds_read_b128 v[128:131], v98
	ds_read_b128 v[136:139], v103 offset:0
	ds_read_b128 v[144:147], v103 offset:2048
	ds_read_b128 v[132:135], v98 offset:512
	ds_read_b128 v[140:143], v103 offset:512
	ds_read_b128 v[148:151], v103 offset:2560
	s_add_i32 m0, s76, 24576
	s_nop 0
	global_load_lds_dwordx4 v[110:111], off
	v_lshl_add_u64 v[110:111], v[110:111], 0, s[78:79]
	s_add_i32 m0, s77, 24576
	s_nop 0
	global_load_lds_dwordx4 v[112:113], off
	v_lshl_add_u64 v[112:113], v[112:113], 0, s[78:79]
	s_add_i32 m0, s77, 25600
	s_nop 0
	global_load_lds_dwordx4 v[114:115], off
	v_lshl_add_u64 v[114:115], v[114:115], 0, s[78:79]
	s_waitcnt lgkmcnt(3)
	v_mfma_f32_16x16x32_bf16 v[120:123], v[128:131], v[136:139], v[120:123]
	v_mfma_f32_16x16x32_bf16 v[124:127], v[128:131], v[144:147], v[124:127]
	s_waitcnt lgkmcnt(0)
	v_mfma_f32_16x16x32_bf16 v[120:123], v[132:135], v[140:143], v[120:123]
	v_mfma_f32_16x16x32_bf16 v[124:127], v[132:135], v[148:151], v[124:127]
	s_waitcnt vmcnt(9)
	s_barrier
; template <class F>
; __device__ __forceinline__ void small_gemm_ks(LAS unsigned char* lds, const bf16_t* A, int lda, const bf16_t* Bt, int ldb, int K, int N, int a_grp_cols, int bx, int G, int tid, const F& f) {
;     ...
;         for (int k0 = 0; k0 < KH; k0 += 32) { const bf16x8 av = *(const bf16x8*)(ap + k0);
; #pragma unroll
;             for (int nt = 0; nt < 2; ++nt) { const bf16x8 bv = *(const bf16x8*)(bp + (size_t)nt * 16 * ldb + k0); acc[nt] = __builtin_amdgcn_mfma_f32_16x16x32_bf16(av, bv, acc[nt], 0, 0, 0); } }
	ds_read_b128 v[152:155], v99
	ds_read_b128 v[160:163], v104 offset:0
	ds_read_b128 v[168:171], v104 offset:2048
	ds_read_b128 v[156:159], v99 offset:512
	ds_read_b128 v[164:167], v104 offset:512
	ds_read_b128 v[172:175], v104 offset:2560
	s_add_i32 m0, s76, 49152
	s_nop 0
	global_load_lds_dwordx4 v[110:111], off
	v_lshl_add_u64 v[110:111], v[110:111], 0, s[78:79]
	s_add_i32 m0, s77, 49152
	s_nop 0
	global_load_lds_dwordx4 v[112:113], off
	v_lshl_add_u64 v[112:113], v[112:113], 0, s[78:79]
	s_add_i32 m0, s77, 50176
	s_nop 0
	global_load_lds_dwordx4 v[114:115], off
	v_lshl_add_u64 v[114:115], v[114:115], 0, s[78:79]
	s_waitcnt lgkmcnt(3)
	v_mfma_f32_16x16x32_bf16 v[120:123], v[152:155], v[160:163], v[120:123]
	v_mfma_f32_16x16x32_bf16 v[124:127], v[152:155], v[168:171], v[124:127]
	s_waitcnt lgkmcnt(0)
	v_mfma_f32_16x16x32_bf16 v[120:123], v[156:159], v[164:167], v[120:123]
	v_mfma_f32_16x16x32_bf16 v[124:127], v[156:159], v[172:175], v[124:127]
	s_waitcnt vmcnt(9)
	s_barrier
	ds_read_b128 v[128:131], v100
	ds_read_b128 v[136:139], v105 offset:0
	ds_read_b128 v[144:147], v105 offset:2048
	ds_read_b128 v[132:135], v100 offset:512
	ds_read_b128 v[140:143], v105 offset:512
	ds_read_b128 v[148:151], v105 offset:2560
	s_add_i32 m0, s76, 73728
	s_nop 0
	global_load_lds_dwordx4 v[110:111], off
	v_lshl_add_u64 v[110:111], v[110:111], 0, s[78:79]
	s_add_i32 m0, s77, 73728
	s_nop 0
	global_load_lds_dwordx4 v[112:113], off
	v_lshl_add_u64 v[112:113], v[112:113], 0, s[78:79]
	s_add_i32 m0, s77, 74752
	s_nop 0
	global_load_lds_dwordx4 v[114:115], off
	v_lshl_add_u64 v[114:115], v[114:115], 0, s[78:79]
	s_waitcnt lgkmcnt(3)
	v_mfma_f32_16x16x32_bf16 v[120:123], v[128:131], v[136:139], v[120:123]
	v_mfma_f32_16x16x32_bf16 v[124:127], v[128:131], v[144:147], v[124:127]
	s_waitcnt lgkmcnt(0)
	v_mfma_f32_16x16x32_bf16 v[120:123], v[132:135], v[140:143], v[120:123]
	v_mfma_f32_16x16x32_bf16 v[124:127], v[132:135], v[148:151], v[124:127]
	s_waitcnt vmcnt(9)
	s_barrier
	ds_read_b128 v[152:155], v96
	ds_read_b128 v[160:163], v101 offset:0
	ds_read_b128 v[168:171], v101 offset:2048
	ds_read_b128 v[156:159], v96 offset:512
	ds_read_b128 v[164:167], v101 offset:512
	ds_read_b128 v[172:175], v101 offset:2560
	s_add_i32 m0, s76, 98304
	s_nop 0
	global_load_lds_dwordx4 v[110:111], off
	v_lshl_add_u64 v[110:111], v[110:111], 0, s[78:79]
	s_add_i32 m0, s77, 98304
	s_nop 0
	global_load_lds_dwordx4 v[112:113], off
	v_lshl_add_u64 v[112:113], v[112:113], 0, s[78:79]
	s_add_i32 m0, s77, 99328
	s_nop 0
	global_load_lds_dwordx4 v[114:115], off
	v_lshl_add_u64 v[114:115], v[114:115], 0, s[78:79]
	s_waitcnt lgkmcnt(3)
	v_mfma_f32_16x16x32_bf16 v[120:123], v[152:155], v[160:163], v[120:123]
	v_mfma_f32_16x16x32_bf16 v[124:127], v[152:155], v[168:171], v[124:127]
	s_waitcnt lgkmcnt(0)
	v_mfma_f32_16x16x32_bf16 v[120:123], v[156:159], v[164:167], v[120:123]
	v_mfma_f32_16x16x32_bf16 v[124:127], v[156:159], v[172:175], v[124:127]
	s_waitcnt vmcnt(9)
	s_barrier
	ds_read_b128 v[128:131], v97
	ds_read_b128 v[136:139], v102 offset:0
	ds_read_b128 v[144:147], v102 offset:2048
	ds_read_b128 v[132:135], v97 offset:512
	ds_read_b128 v[140:143], v102 offset:512
	ds_read_b128 v[148:151], v102 offset:2560
	s_add_i32 m0, s76, 0
	s_nop 0
	global_load_lds_dwordx4 v[110:111], off
	v_lshl_add_u64 v[110:111], v[110:111], 0, s[78:79]
	s_add_i32 m0, s77, 0
	s_nop 0
	global_load_lds_dwordx4 v[112:113], off
	v_lshl_add_u64 v[112:113], v[112:113], 0, s[78:79]
	s_add_i32 m0, s77, 1024
	s_nop 0
	global_load_lds_dwordx4 v[114:115], off
	v_lshl_add_u64 v[114:115], v[114:115], 0, s[78:79]
	s_waitcnt lgkmcnt(3)
	v_mfma_f32_16x16x32_bf16 v[120:123], v[128:131], v[136:139], v[120:123]
	v_mfma_f32_16x16x32_bf16 v[124:127], v[128:131], v[144:147], v[124:127]
	s_waitcnt lgkmcnt(0)
	v_mfma_f32_16x16x32_bf16 v[120:123], v[132:135], v[140:143], v[120:123]
	v_mfma_f32_16x16x32_bf16 v[124:127], v[132:135], v[148:151], v[124:127]
	s_waitcnt vmcnt(9)
	s_barrier
	ds_read_b128 v[152:155], v98
	ds_read_b128 v[160:163], v103 offset:0
	ds_read_b128 v[168:171], v103 offset:2048
	ds_read_b128 v[156:159], v98 offset:512
	ds_read_b128 v[164:167], v103 offset:512
	ds_read_b128 v[172:175], v103 offset:2560
	s_add_i32 m0, s76, 24576
	s_nop 0
	global_load_lds_dwordx4 v[110:111], off
	v_lshl_add_u64 v[110:111], v[110:111], 0, s[78:79]
	s_add_i32 m0, s77, 24576
	s_nop 0
	global_load_lds_dwordx4 v[112:113], off
	v_lshl_add_u64 v[112:113], v[112:113], 0, s[78:79]
	s_add_i32 m0, s77, 25600
	s_nop 0
	global_load_lds_dwordx4 v[114:115], off
	v_lshl_add_u64 v[114:115], v[114:115], 0, s[78:79]
	s_waitcnt lgkmcnt(3)
	v_mfma_f32_16x16x32_bf16 v[120:123], v[152:155], v[160:163], v[120:123]
	v_mfma_f32_16x16x32_bf16 v[124:127], v[152:155], v[168:171], v[124:127]
	s_waitcnt lgkmcnt(0)
	v_mfma_f32_16x16x32_bf16 v[120:123], v[156:159], v[164:167], v[120:123]
	v_mfma_f32_16x16x32_bf16 v[124:127], v[156:159], v[172:175], v[124:127]
	s_waitcnt vmcnt(9)
	s_barrier
; #define LAS __attribute__((address_space(3)))
; #define LDS_SYNC() do { asm volatile("s_waitcnt lgkmcnt(0)" ::: "memory"); __builtin_amdgcn_s_barrier(); asm volatile("" ::: "memory"); } while (0)
; template <class F>
; __device__ __forceinline__ void small_gemm_ks(LAS unsigned char* lds, const bf16_t* A, int lda, const bf16_t* Bt, int ldb, int K, int N, int a_grp_cols, int bx, int G, int tid, const F& f) {
;     ...
;         for (int k0 = 0; k0 < KH; k0 += 32) { const bf16x8 av = *(const bf16x8*)(ap + k0);
; #pragma unroll
;             for (int nt = 0; nt < 2; ++nt) { const bf16x8 bv = *(const bf16x8*)(bp + (size_t)nt * 16 * ldb + k0); acc[nt] = __builtin_amdgcn_mfma_f32_16x16x32_bf16(av, bv, acc[nt], 0, 0, 0); } }
;         if (kh == 1) { *(LAS f32x4*)(lds + ((wq * 2 + 0) * 64 + lane) * 16) = acc[0]; *(LAS f32x4*)(lds + ((wq * 2 + 1) * 64 + lane) * 16) = acc[1]; }
;         LDS_SYNC();
;         if (kh == 0) {
; #pragma unroll
;             for (int nt = 0; nt < 2; ++nt) { const f32x4 o = acc[nt] + *(const LAS f32x4*)(lds + ((wq * 2 + nt) * 64 + lane) * 16);
; #pragma unroll
;                 for (int j = 0; j < 4; ++j) f(row0 + 4 * g + j, n0 + 16 * nt + c, o[j]); }
;         }
;         LDS_SYNC();
	ds_read_b128 v[128:131], v99
	ds_read_b128 v[136:139], v104 offset:0
	ds_read_b128 v[144:147], v104 offset:2048
	ds_read_b128 v[132:135], v99 offset:512
	ds_read_b128 v[140:143], v104 offset:512
	ds_read_b128 v[148:151], v104 offset:2560
	s_waitcnt lgkmcnt(3)
	v_mfma_f32_16x16x32_bf16 v[120:123], v[128:131], v[136:139], v[120:123]
	v_mfma_f32_16x16x32_bf16 v[124:127], v[128:131], v[144:147], v[124:127]
	s_waitcnt lgkmcnt(0)
	v_mfma_f32_16x16x32_bf16 v[120:123], v[132:135], v[140:143], v[120:123]
	v_mfma_f32_16x16x32_bf16 v[124:127], v[132:135], v[148:151], v[124:127]
	s_waitcnt vmcnt(6)
	s_barrier
	ds_read_b128 v[152:155], v100
	ds_read_b128 v[160:163], v105 offset:0
	ds_read_b128 v[168:171], v105 offset:2048
	ds_read_b128 v[156:159], v100 offset:512
	ds_read_b128 v[164:167], v105 offset:512
	ds_read_b128 v[172:175], v105 offset:2560
	s_waitcnt lgkmcnt(3)
	v_mfma_f32_16x16x32_bf16 v[120:123], v[152:155], v[160:163], v[120:123]
	v_mfma_f32_16x16x32_bf16 v[124:127], v[152:155], v[168:171], v[124:127]
	s_waitcnt lgkmcnt(0)
	v_mfma_f32_16x16x32_bf16 v[120:123], v[156:159], v[164:167], v[120:123]
	v_mfma_f32_16x16x32_bf16 v[124:127], v[156:159], v[172:175], v[124:127]
	s_waitcnt vmcnt(3)
	s_barrier
	ds_read_b128 v[128:131], v96
	ds_read_b128 v[136:139], v101 offset:0
	ds_read_b128 v[144:147], v101 offset:2048
	ds_read_b128 v[132:135], v96 offset:512
	ds_read_b128 v[140:143], v101 offset:512
	ds_read_b128 v[148:151], v101 offset:2560
	s_waitcnt lgkmcnt(3)
	v_mfma_f32_16x16x32_bf16 v[120:123], v[128:131], v[136:139], v[120:123]
	v_mfma_f32_16x16x32_bf16 v[124:127], v[128:131], v[144:147], v[124:127]
	s_waitcnt lgkmcnt(0)
	v_mfma_f32_16x16x32_bf16 v[120:123], v[132:135], v[140:143], v[120:123]
	v_mfma_f32_16x16x32_bf16 v[124:127], v[132:135], v[148:151], v[124:127]
	s_waitcnt vmcnt(0)
	s_barrier
	ds_read_b128 v[152:155], v97
	ds_read_b128 v[160:163], v102 offset:0
	ds_read_b128 v[168:171], v102 offset:2048
	ds_read_b128 v[156:159], v97 offset:512
	ds_read_b128 v[164:167], v102 offset:512
	ds_read_b128 v[172:175], v102 offset:2560
	s_waitcnt lgkmcnt(3)
	v_mfma_f32_16x16x32_bf16 v[120:123], v[152:155], v[160:163], v[120:123]
	v_mfma_f32_16x16x32_bf16 v[124:127], v[152:155], v[168:171], v[124:127]
	s_waitcnt lgkmcnt(0)
	v_mfma_f32_16x16x32_bf16 v[120:123], v[156:159], v[164:167], v[120:123]
	v_mfma_f32_16x16x32_bf16 v[124:127], v[156:159], v[172:175], v[124:127]
	s_barrier
	s_lshl_b32 s59, s82, 11
	s_lshl_b32 s62, s83, 1
	s_add_i32 s59, s59, s62
	s_add_u32 s60, s54, s59
	s_addc_u32 s61, s55, 0
	s_add_u32 s60, s60, 0x5700000
	s_addc_u32 s61, s61, 0
	v_lshl_add_u64 v[176:177], s[60:61], 0, v[106:107]
	s_mov_b32 s62, 0x1000
	s_mov_b32 s63, 0
	v_lshl_add_u64 v[178:179], v[176:177], 0, s[62:63]
	s_cmp_eq_u32 s70, 0
	s_cbranch_scc1 .Lsg_dn0_lo
	s_nop 4
	ds_write_b128 v109, v[120:123]
	ds_write_b128 v109, v[124:127] offset:1024
	s_waitcnt lgkmcnt(0)
	s_barrier
	s_branch .Lsg_dn0_done
.Lsg_dn0_lo:
	s_barrier
	ds_read_b128 v[180:183], v109
	ds_read_b128 v[184:187], v109 offset:1024
	s_waitcnt lgkmcnt(0)
	v_add_f32_e32 v120, v120, v180
	v_add_f32_e32 v121, v121, v181
	v_add_f32_e32 v122, v122, v182
	v_add_f32_e32 v123, v123, v183
	v_add_f32_e32 v124, v124, v184
	v_add_f32_e32 v125, v125, v185
	v_add_f32_e32 v126, v126, v186
	v_add_f32_e32 v127, v127, v187
	v_cvt_pk_bf16_f32 v120, v120, v120
	v_cvt_pk_bf16_f32 v121, v121, v121
	v_cvt_pk_bf16_f32 v122, v122, v122
	v_cvt_pk_bf16_f32 v123, v123, v123
	v_cvt_pk_bf16_f32 v124, v124, v124
	v_cvt_pk_bf16_f32 v125, v125, v125
	v_cvt_pk_bf16_f32 v126, v126, v126
	v_cvt_pk_bf16_f32 v127, v127, v127
	global_store_short v[176:177], v120, off offset:0
	global_store_short v[176:177], v121, off offset:2048
	global_store_short v[178:179], v122, off offset:0
	global_store_short v[178:179], v123, off offset:2048
	global_store_short v[176:177], v124, off offset:32
	global_store_short v[176:177], v125, off offset:2080
	global_store_short v[178:179], v126, off offset:32
	global_store_short v[178:179], v127, off offset:2080
.Lsg_dn0_done:
	s_waitcnt lgkmcnt(0)
	s_barrier
	s_add_i32 s81, s81, s56
	s_cmpk_lt_i32 s81, 0x100
	s_cbranch_scc1 .Lsg_dn0_tile

; template <class F>
; __device__ __forceinline__ void small_gemm_ks(LAS unsigned char* lds, const bf16_t* A, int lda, const bf16_t* Bt, int ldb, int K, int N, int a_grp_cols, int bx, int G, int tid, const F& f) {
;     const int lane = tid & 63, w = __builtin_amdgcn_readfirstlane(tid >> 6), c = lane & 15, g = lane >> 4, kh = w >> 2, wq = w & 3, wm = wq >> 1, wn = wq & 1;
;     const int ntn = N / 64, ntiles = (MS / 32) * ntn, KH = K / 2;
;     for (int t = bx; t < ntiles; t += G) {
;         const int row0 = MP + (t / ntn) * 32 + wm * 16, n0 = (t % ntn) * 64 + wn * 32;
;         const bf16_t* ap = A + (size_t)(row0 + c) * lda + (n0 >> 8) * a_grp_cols + kh * KH + 8 * g;
;         const bf16_t* bp = Bt + (size_t)(n0 + c) * ldb + kh * KH + 8 * g;
;         f32x4 acc[2] = {(f32x4){0.f, 0.f, 0.f, 0.f}, (f32x4){0.f, 0.f, 0.f, 0.f}};
; #pragma unroll 8
;         for (int k0 = 0; k0 < KH; k0 += 32) { const bf16x8 av = *(const bf16x8*)(ap + k0);
; #pragma unroll
;             for (int nt = 0; nt < 2; ++nt) { const bf16x8 bv = *(const bf16x8*)(bp + (size_t)nt * 16 * ldb + k0); acc[nt] = __builtin_amdgcn_mfma_f32_16x16x32_bf16(av, bv, acc[nt], 0, 0, 0); } }
.LBB0_1988:
	s_waitcnt lgkmcnt(0)
	s_add_u32 s0, s6, 0x1d00000
	s_addc_u32 s1, s7, 0
	s_add_u32 s3, s6, 0x9900000
	s_addc_u32 s4, s7, 0
	s_add_u32 s10, s6, 0x5700000
	s_addc_u32 s11, s7, 0
	v_readfirstlane_b32 s6, v20
	s_and_b64 vcc, exec, s[88:89]
	v_and_b32_e32 v14, 15, v20
	s_cbranch_vccnz .LBB0_1995
	v_readfirstlane_b32 s68, v208
	v_and_b32_e32 v86, 63, v208
	s_nop 3
	s_lshr_b32 s68, s68, 6
	v_and_b32_e32 v87, 7, v86
	v_lshrrev_b32_e32 v88, 3, v86
	s_mov_b32 s69, 5632
	v_mul_lo_u32 v90, v87, s69
	v_lshl_add_u32 v90, v88, 4, v90
	v_mov_b32_e32 v91, 0
	s_mov_b32 s69, 5632
	v_mul_lo_u32 v92, v87, s69
	v_lshl_add_u32 v92, v88, 4, v92
	v_mov_b32_e32 v93, 0
	v_and_b32_e32 v87, 15, v86
	v_lshrrev_b32_e32 v88, 4, v86
	v_lshrrev_b32_e32 v89, 3, v87
	v_lshlrev_b32_e32 v89, 10, v89
	v_lshl_add_u32 v89, v88, 7, v89
	v_and_b32_e32 v94, 7, v87
	v_lshl_add_u32 v89, v94, 4, v89
	s_lshr_b32 s70, s68, 2
	s_bfe_u32 s71, s68, 0x10001
	s_and_b32 s72, s68, 1
	s_lshl_b32 s73, s70, 12
	s_lshl_b32 s74, s71, 11
	s_add_i32 s73, s73, s74
	s_lshl_b32 s74, s70, 13
	s_lshl_b32 s75, s72, 12
	s_add_i32 s74, s74, s75
	s_add_i32 s74, s74, 0x2000
	v_add_u32_e32 v96, s73, v89
	v_add_u32_e32 v101, s74, v89
	v_add_u32_e32 v97, s73, v89
	v_add_u32_e32 v102, s74, v89
	v_add_u32_e32 v98, s73, v89
	v_add_u32_e32 v103, s74, v89
	v_add_u32_e32 v99, s73, v89
	v_add_u32_e32 v104, s74, v89
	v_add_u32_e32 v100, s73, v89
	v_add_u32_e32 v105, s74, v89
	v_add_u32_e32 v97, 24576, v97
	v_add_u32_e32 v102, 24576, v102
	v_add_u32_e32 v98, 49152, v98
	v_add_u32_e32 v103, 49152, v103
	v_add_u32_e32 v99, 73728, v99
	v_add_u32_e32 v104, 73728, v104
	v_add_u32_e32 v100, 98304, v100
	v_add_u32_e32 v105, 98304, v105
	s_lshl_b32 s75, s71, 4
	v_lshl_add_u32 v106, v88, 2, s75
	v_lshlrev_b32_e32 v106, 11, v106
	s_lshl_b32 s75, s72, 5
	v_add_u32_e32 v107, s75, v87
	v_lshl_add_u32 v106, v107, 1, v106
	v_lshlrev_b32_e32 v108, 2, v107
	v_mov_b32_e32 v107, 0
	s_and_b32 s75, s68, 3
	s_lshl_b32 s75, s75, 11
	v_lshl_add_u32 v109, v86, 4, s75
	s_lshl_b32 s76, s68, 10
	s_lshl_b32 s77, s68, 11
	s_add_i32 s77, s77, 0x2000
	s_mov_b32 s78, 0x80
	s_mov_b32 s79, 0
	s_and_b32 s80, s68, 3
	s_mov_b32 s81, s2
.Lsg_dn1_tile:
	s_lshr_b32 s82, s81, 4
	s_lshl_b32 s82, s82, 5
	s_add_i32 s82, s82, 0x4000
	s_and_b32 s83, s81, 15
	s_lshl_b32 s83, s83, 6
	s_lshl_b32 s59, s80, 3
	s_add_i32 s59, s59, s82
	s_mul_i32 s60, s59, 5632
	s_mul_hi_u32 s61, s59, 5632
	s_mul_i32 s62, s70, 2816
	s_add_u32 s60, s60, s62
	s_addc_u32 s61, s61, 0
	s_add_u32 s60, s60, s54
	s_addc_u32 s61, s61, s55
	s_add_u32 s60, s60, 0x9900000
	s_addc_u32 s61, s61, 0
	v_lshl_add_u64 v[110:111], s[60:61], 0, v[90:91]
	s_lshl_b32 s59, s80, 4
	s_add_i32 s59, s59, s83
	s_mul_i32 s60, s59, 5632
	s_mul_i32 s62, s70, 2816
	s_add_u32 s60, s60, s62
	s_add_u32 s60, s60, s54
	s_addc_u32 s61, s55, 0
	s_add_u32 s60, s60, 0x1d00000
	s_addc_u32 s61, s61, 0
	v_lshl_add_u64 v[112:113], s[60:61], 0, v[92:93]
	s_add_u32 s60, s60, 45056
	s_addc_u32 s61, s61, 0
	v_lshl_add_u64 v[114:115], s[60:61], 0, v[92:93]
	s_waitcnt vmcnt(0)
	v_mov_b32_e32 v120, 0
	v_mov_b32_e32 v121, 0
	v_mov_b32_e32 v122, 0
	v_mov_b32_e32 v123, 0
	v_mov_b32_e32 v124, 0
	v_mov_b32_e32 v125, 0
	v_mov_b32_e32 v126, 0
	v_mov_b32_e32 v127, 0
	s_add_i32 m0, s76, 0
	s_nop 0
	global_load_lds_dwordx4 v[110:111], off
	v_lshl_add_u64 v[110:111], v[110:111], 0, s[78:79]
	s_add_i32 m0, s77, 0
	s_nop 0
	global_load_lds_dwordx4 v[112:113], off
	v_lshl_add_u64 v[112:113], v[112:113], 0, s[78:79]
	s_add_i32 m0, s77, 1024
	s_nop 0
	global_load_lds_dwordx4 v[114:115], off
	v_lshl_add_u64 v[114:115], v[114:115], 0, s[78:79]
	s_add_i32 m0, s76, 24576
	s_nop 0
	global_load_lds_dwordx4 v[110:111], off
	v_lshl_add_u64 v[110:111], v[110:111], 0, s[78:79]
	s_add_i32 m0, s77, 24576
	s_nop 0
	global_load_lds_dwordx4 v[112:113], off
	v_lshl_add_u64 v[112:113], v[112:113], 0, s[78:79]
	s_add_i32 m0, s77, 25600
	s_nop 0
	global_load_lds_dwordx4 v[114:115], off
	v_lshl_add_u64 v[114:115], v[114:115], 0, s[78:79]
	s_add_i32 m0, s76, 49152
	s_nop 0
	global_load_lds_dwordx4 v[110:111], off
	v_lshl_add_u64 v[110:111], v[110:111], 0, s[78:79]
	s_add_i32 m0, s77, 49152
	s_nop 0
	global_load_lds_dwordx4 v[112:113], off
	v_lshl_add_u64 v[112:113], v[112:113], 0, s[78:79]
	s_add_i32 m0, s77, 50176
	s_nop 0
	global_load_lds_dwordx4 v[114:115], off
	v_lshl_add_u64 v[114:115], v[114:115], 0, s[78:79]
	s_add_i32 m0, s76, 73728
	s_nop 0
	global_load_lds_dwordx4 v[110:111], off
	v_lshl_add_u64 v[110:111], v[110:111], 0, s[78:79]
	s_add_i32 m0, s77, 73728
	s_nop 0
	global_load_lds_dwordx4 v[112:113], off
	v_lshl_add_u64 v[112:113], v[112:113], 0, s[78:79]
	s_add_i32 m0, s77, 74752
	s_nop 0
	global_load_lds_dwordx4 v[114:115], off
	v_lshl_add_u64 v[114:115], v[114:115], 0, s[78:79]
	s_waitcnt vmcnt(9)
	s_barrier
	ds_read_b128 v[128:131], v96
	ds_read_b128 v[136:139], v101 offset:0
	ds_read_b128 v[144:147], v101 offset:2048
	ds_read_b128 v[132:135], v96 offset:512
	ds_read_b128 v[140:143], v101 offset:512
	ds_read_b128 v[148:151], v101 offset:2560
	s_add_i32 m0, s76, 98304
	s_nop 0
	global_load_lds_dwordx4 v[110:111], off
	v_lshl_add_u64 v[110:111], v[110:111], 0, s[78:79]
	s_add_i32 m0, s77, 98304
	s_nop 0
	global_load_lds_dwordx4 v[112:113], off
	v_lshl_add_u64 v[112:113], v[112:113], 0, s[78:79]
	s_add_i32 m0, s77, 99328
	s_nop 0
	global_load_lds_dwordx4 v[114:115], off
	v_lshl_add_u64 v[114:115], v[114:115], 0, s[78:79]
	s_waitcnt lgkmcnt(3)
	v_mfma_f32_16x16x32_bf16 v[120:123], v[128:131], v[136:139], v[120:123]
	v_mfma_f32_16x16x32_bf16 v[124:127], v[128:131], v[144:147], v[124:127]
	s_waitcnt lgkmcnt(0)
	v_mfma_f32_16x16x32_bf16 v[120:123], v[132:135], v[140:143], v[120:123]
	v_mfma_f32_16x16x32_bf16 v[124:127], v[132:135], v[148:151], v[124:127]
	s_waitcnt vmcnt(9)
	s_barrier
; template <class F>
; __device__ __forceinline__ void small_gemm_ks(LAS unsigned char* lds, const bf16_t* A, int lda, const bf16_t* Bt, int ldb, int K, int N, int a_grp_cols, int bx, int G, int tid, const F& f) {
;     ...
;         for (int k0 = 0; k0 < KH; k0 += 32) { const bf16x8 av = *(const bf16x8*)(ap + k0);
; #pragma unroll
;             for (int nt = 0; nt < 2; ++nt) { const bf16x8 bv = *(const bf16x8*)(bp + (size_t)nt * 16 * ldb + k0); acc[nt] = __builtin_amdgcn_mfma_f32_16x16x32_bf16(av, bv, acc[nt], 0, 0, 0); } }
	ds_read_b128 v[152:155], v97
	ds_read_b128 v[160:163], v102 offset:0
	ds_read_b128 v[168:171], v102 offset:2048
	ds_read_b128 v[156:159], v97 offset:512
	ds_read_b128 v[164:167], v102 offset:512
	ds_read_b128 v[172:175], v102 offset:2560
	s_add_i32 m0, s76, 0
	s_nop 0
	global_load_lds_dwordx4 v[110:111], off
	v_lshl_add_u64 v[110:111], v[110:111], 0, s[78:79]
	s_add_i32 m0, s77, 0
	s_nop 0
	global_load_lds_dwordx4 v[112:113], off
	v_lshl_add_u64 v[112:113], v[112:113], 0, s[78:79]
	s_add_i32 m0, s77, 1024
	s_nop 0
	global_load_lds_dwordx4 v[114:115], off
	v_lshl_add_u64 v[114:115], v[114:115], 0, s[78:79]
	s_waitcnt lgkmcnt(3)
	v_mfma_f32_16x16x32_bf16 v[120:123], v[152:155], v[160:163], v[120:123]
	v_mfma_f32_16x16x32_bf16 v[124:127], v[152:155], v[168:171], v[124:127]
	s_waitcnt lgkmcnt(0)
	v_mfma_f32_16x16x32_bf16 v[120:123], v[156:159], v[164:167], v[120:123]
	v_mfma_f32_16x16x32_bf16 v[124:127], v[156:159], v[172:175], v[124:127]
	s_waitcnt vmcnt(9)
	s_barrier
	ds_read_b128 v[128:131], v98
	ds_read_b128 v[136:139], v103 offset:0
	ds_read_b128 v[144:147], v103 offset:2048
	ds_read_b128 v[132:135], v98 offset:512
	ds_read_b128 v[140:143], v103 offset:512
	ds_read_b128 v[148:151], v103 offset:2560
	s_add_i32 m0, s76, 24576
	s_nop 0
	global_load_lds_dwordx4 v[110:111], off
	v_lshl_add_u64 v[110:111], v[110:111], 0, s[78:79]
	s_add_i32 m0, s77, 24576
	s_nop 0
	global_load_lds_dwordx4 v[112:113], off
	v_lshl_add_u64 v[112:113], v[112:113], 0, s[78:79]
	s_add_i32 m0, s77, 25600
	s_nop 0
	global_load_lds_dwordx4 v[114:115], off
	v_lshl_add_u64 v[114:115], v[114:115], 0, s[78:79]
	s_waitcnt lgkmcnt(3)
	v_mfma_f32_16x16x32_bf16 v[120:123], v[128:131], v[136:139], v[120:123]
	v_mfma_f32_16x16x32_bf16 v[124:127], v[128:131], v[144:147], v[124:127]
	s_waitcnt lgkmcnt(0)
	v_mfma_f32_16x16x32_bf16 v[120:123], v[132:135], v[140:143], v[120:123]
	v_mfma_f32_16x16x32_bf16 v[124:127], v[132:135], v[148:151], v[124:127]
	s_waitcnt vmcnt(9)
	s_barrier
	ds_read_b128 v[152:155], v99
	ds_read_b128 v[160:163], v104 offset:0
	ds_read_b128 v[168:171], v104 offset:2048
	ds_read_b128 v[156:159], v99 offset:512
	ds_read_b128 v[164:167], v104 offset:512
	ds_read_b128 v[172:175], v104 offset:2560
	s_add_i32 m0, s76, 49152
	s_nop 0
	global_load_lds_dwordx4 v[110:111], off
	v_lshl_add_u64 v[110:111], v[110:111], 0, s[78:79]
	s_add_i32 m0, s77, 49152
	s_nop 0
	global_load_lds_dwordx4 v[112:113], off
	v_lshl_add_u64 v[112:113], v[112:113], 0, s[78:79]
	s_add_i32 m0, s77, 50176
	s_nop 0
	global_load_lds_dwordx4 v[114:115], off
	v_lshl_add_u64 v[114:115], v[114:115], 0, s[78:79]
	s_waitcnt lgkmcnt(3)
	v_mfma_f32_16x16x32_bf16 v[120:123], v[152:155], v[160:163], v[120:123]
	v_mfma_f32_16x16x32_bf16 v[124:127], v[152:155], v[168:171], v[124:127]
	s_waitcnt lgkmcnt(0)
	v_mfma_f32_16x16x32_bf16 v[120:123], v[156:159], v[164:167], v[120:123]
	v_mfma_f32_16x16x32_bf16 v[124:127], v[156:159], v[172:175], v[124:127]
	s_waitcnt vmcnt(9)
	s_barrier
	ds_read_b128 v[128:131], v100
	ds_read_b128 v[136:139], v105 offset:0
	ds_read_b128 v[144:147], v105 offset:2048
	ds_read_b128 v[132:135], v100 offset:512
	ds_read_b128 v[140:143], v105 offset:512
	ds_read_b128 v[148:151], v105 offset:2560
	s_add_i32 m0, s76, 73728
	s_nop 0
	global_load_lds_dwordx4 v[110:111], off
	v_lshl_add_u64 v[110:111], v[110:111], 0, s[78:79]
	s_add_i32 m0, s77, 73728
	s_nop 0
	global_load_lds_dwordx4 v[112:113], off
	v_lshl_add_u64 v[112:113], v[112:113], 0, s[78:79]
	s_add_i32 m0, s77, 74752
	s_nop 0
	global_load_lds_dwordx4 v[114:115], off
	v_lshl_add_u64 v[114:115], v[114:115], 0, s[78:79]
	s_waitcnt lgkmcnt(3)
	v_mfma_f32_16x16x32_bf16 v[120:123], v[128:131], v[136:139], v[120:123]
	v_mfma_f32_16x16x32_bf16 v[124:127], v[128:131], v[144:147], v[124:127]
	s_waitcnt lgkmcnt(0)
	v_mfma_f32_16x16x32_bf16 v[120:123], v[132:135], v[140:143], v[120:123]
	v_mfma_f32_16x16x32_bf16 v[124:127], v[132:135], v[148:151], v[124:127]
	s_waitcnt vmcnt(9)
	s_barrier
	ds_read_b128 v[152:155], v96
	ds_read_b128 v[160:163], v101 offset:0
	ds_read_b128 v[168:171], v101 offset:2048
	ds_read_b128 v[156:159], v96 offset:512
	ds_read_b128 v[164:167], v101 offset:512
	ds_read_b128 v[172:175], v101 offset:2560
	s_add_i32 m0, s76, 98304
	s_nop 0
	global_load_lds_dwordx4 v[110:111], off
	v_lshl_add_u64 v[110:111], v[110:111], 0, s[78:79]
	s_add_i32 m0, s77, 98304
	s_nop 0
	global_load_lds_dwordx4 v[112:113], off
	v_lshl_add_u64 v[112:113], v[112:113], 0, s[78:79]
	s_add_i32 m0, s77, 99328
	s_nop 0
	global_load_lds_dwordx4 v[114:115], off
	v_lshl_add_u64 v[114:115], v[114:115], 0, s[78:79]
	s_waitcnt lgkmcnt(3)
	v_mfma_f32_16x16x32_bf16 v[120:123], v[152:155], v[160:163], v[120:123]
	v_mfma_f32_16x16x32_bf16 v[124:127], v[152:155], v[168:171], v[124:127]
	s_waitcnt lgkmcnt(0)
	v_mfma_f32_16x16x32_bf16 v[120:123], v[156:159], v[164:167], v[120:123]
	v_mfma_f32_16x16x32_bf16 v[124:127], v[156:159], v[172:175], v[124:127]
	s_waitcnt vmcnt(9)
	s_barrier
	ds_read_b128 v[128:131], v97
	ds_read_b128 v[136:139], v102 offset:0
	ds_read_b128 v[144:147], v102 offset:2048
	ds_read_b128 v[132:135], v97 offset:512
	ds_read_b128 v[140:143], v102 offset:512
	ds_read_b128 v[148:151], v102 offset:2560
	s_add_i32 m0, s76, 0
	s_nop 0
	global_load_lds_dwordx4 v[110:111], off
	v_lshl_add_u64 v[110:111], v[110:111], 0, s[78:79]
	s_add_i32 m0, s77, 0
	s_nop 0
	global_load_lds_dwordx4 v[112:113], off
	v_lshl_add_u64 v[112:113], v[112:113], 0, s[78:79]
	s_add_i32 m0, s77, 1024
	s_nop 0
	global_load_lds_dwordx4 v[114:115], off
	v_lshl_add_u64 v[114:115], v[114:115], 0, s[78:79]
	s_waitcnt lgkmcnt(3)
	v_mfma_f32_16x16x32_bf16 v[120:123], v[128:131], v[136:139], v[120:123]
	v_mfma_f32_16x16x32_bf16 v[124:127], v[128:131], v[144:147], v[124:127]
	s_waitcnt lgkmcnt(0)
	v_mfma_f32_16x16x32_bf16 v[120:123], v[132:135], v[140:143], v[120:123]
	v_mfma_f32_16x16x32_bf16 v[124:127], v[132:135], v[148:151], v[124:127]
	s_waitcnt vmcnt(9)
	s_barrier
; template <class F>
; __device__ __forceinline__ void small_gemm_ks(LAS unsigned char* lds, const bf16_t* A, int lda, const bf16_t* Bt, int ldb, int K, int N, int a_grp_cols, int bx, int G, int tid, const F& f) {
;     ...
;         for (int k0 = 0; k0 < KH; k0 += 32) { const bf16x8 av = *(const bf16x8*)(ap + k0);
; #pragma unroll
;             for (int nt = 0; nt < 2; ++nt) { const bf16x8 bv = *(const bf16x8*)(bp + (size_t)nt * 16 * ldb + k0); acc[nt] = __builtin_amdgcn_mfma_f32_16x16x32_bf16(av, bv, acc[nt], 0, 0, 0); } }
	ds_read_b128 v[152:155], v98
	ds_read_b128 v[160:163], v103 offset:0
	ds_read_b128 v[168:171], v103 offset:2048
	ds_read_b128 v[156:159], v98 offset:512
	ds_read_b128 v[164:167], v103 offset:512
	ds_read_b128 v[172:175], v103 offset:2560
	s_add_i32 m0, s76, 24576
	s_nop 0
	global_load_lds_dwordx4 v[110:111], off
	v_lshl_add_u64 v[110:111], v[110:111], 0, s[78:79]
	s_add_i32 m0, s77, 24576
	s_nop 0
	global_load_lds_dwordx4 v[112:113], off
	v_lshl_add_u64 v[112:113], v[112:113], 0, s[78:79]
	s_add_i32 m0, s77, 25600
	s_nop 0
	global_load_lds_dwordx4 v[114:115], off
	v_lshl_add_u64 v[114:115], v[114:115], 0, s[78:79]
	s_waitcnt lgkmcnt(3)
	v_mfma_f32_16x16x32_bf16 v[120:123], v[152:155], v[160:163], v[120:123]
	v_mfma_f32_16x16x32_bf16 v[124:127], v[152:155], v[168:171], v[124:127]
	s_waitcnt lgkmcnt(0)
	v_mfma_f32_16x16x32_bf16 v[120:123], v[156:159], v[164:167], v[120:123]
	v_mfma_f32_16x16x32_bf16 v[124:127], v[156:159], v[172:175], v[124:127]
	s_waitcnt vmcnt(9)
	s_barrier
	ds_read_b128 v[128:131], v99
	ds_read_b128 v[136:139], v104 offset:0
	ds_read_b128 v[144:147], v104 offset:2048
	ds_read_b128 v[132:135], v99 offset:512
	ds_read_b128 v[140:143], v104 offset:512
	ds_read_b128 v[148:151], v104 offset:2560
	s_add_i32 m0, s76, 49152
	s_nop 0
	global_load_lds_dwordx4 v[110:111], off
	v_lshl_add_u64 v[110:111], v[110:111], 0, s[78:79]
	s_add_i32 m0, s77, 49152
	s_nop 0
	global_load_lds_dwordx4 v[112:113], off
	v_lshl_add_u64 v[112:113], v[112:113], 0, s[78:79]
	s_add_i32 m0, s77, 50176
	s_nop 0
	global_load_lds_dwordx4 v[114:115], off
	v_lshl_add_u64 v[114:115], v[114:115], 0, s[78:79]
	s_waitcnt lgkmcnt(3)
	v_mfma_f32_16x16x32_bf16 v[120:123], v[128:131], v[136:139], v[120:123]
	v_mfma_f32_16x16x32_bf16 v[124:127], v[128:131], v[144:147], v[124:127]
	s_waitcnt lgkmcnt(0)
	v_mfma_f32_16x16x32_bf16 v[120:123], v[132:135], v[140:143], v[120:123]
	v_mfma_f32_16x16x32_bf16 v[124:127], v[132:135], v[148:151], v[124:127]
	s_waitcnt vmcnt(9)
	s_barrier
	ds_read_b128 v[152:155], v100
	ds_read_b128 v[160:163], v105 offset:0
	ds_read_b128 v[168:171], v105 offset:2048
	ds_read_b128 v[156:159], v100 offset:512
	ds_read_b128 v[164:167], v105 offset:512
	ds_read_b128 v[172:175], v105 offset:2560
	s_add_i32 m0, s76, 73728
	s_nop 0
	global_load_lds_dwordx4 v[110:111], off
	v_lshl_add_u64 v[110:111], v[110:111], 0, s[78:79]
	s_add_i32 m0, s77, 73728
	s_nop 0
	global_load_lds_dwordx4 v[112:113], off
	v_lshl_add_u64 v[112:113], v[112:113], 0, s[78:79]
	s_add_i32 m0, s77, 74752
	s_nop 0
	global_load_lds_dwordx4 v[114:115], off
	v_lshl_add_u64 v[114:115], v[114:115], 0, s[78:79]
	s_waitcnt lgkmcnt(3)
	v_mfma_f32_16x16x32_bf16 v[120:123], v[152:155], v[160:163], v[120:123]
	v_mfma_f32_16x16x32_bf16 v[124:127], v[152:155], v[168:171], v[124:127]
	s_waitcnt lgkmcnt(0)
	v_mfma_f32_16x16x32_bf16 v[120:123], v[156:159], v[164:167], v[120:123]
	v_mfma_f32_16x16x32_bf16 v[124:127], v[156:159], v[172:175], v[124:127]
	s_waitcnt vmcnt(9)
	s_barrier
	ds_read_b128 v[128:131], v96
	ds_read_b128 v[136:139], v101 offset:0
	ds_read_b128 v[144:147], v101 offset:2048
	ds_read_b128 v[132:135], v96 offset:512
	ds_read_b128 v[140:143], v101 offset:512
	ds_read_b128 v[148:151], v101 offset:2560
	s_add_i32 m0, s76, 98304
	s_nop 0
	global_load_lds_dwordx4 v[110:111], off
	v_lshl_add_u64 v[110:111], v[110:111], 0, s[78:79]
	s_add_i32 m0, s77, 98304
	s_nop 0
	global_load_lds_dwordx4 v[112:113], off
	v_lshl_add_u64 v[112:113], v[112:113], 0, s[78:79]
	s_add_i32 m0, s77, 99328
	s_nop 0
	global_load_lds_dwordx4 v[114:115], off
	v_lshl_add_u64 v[114:115], v[114:115], 0, s[78:79]
	s_waitcnt lgkmcnt(3)
	v_mfma_f32_16x16x32_bf16 v[120:123], v[128:131], v[136:139], v[120:123]
	v_mfma_f32_16x16x32_bf16 v[124:127], v[128:131], v[144:147], v[124:127]
	s_waitcnt lgkmcnt(0)
	v_mfma_f32_16x16x32_bf16 v[120:123], v[132:135], v[140:143], v[120:123]
	v_mfma_f32_16x16x32_bf16 v[124:127], v[132:135], v[148:151], v[124:127]
	s_waitcnt vmcnt(9)
	s_barrier
	ds_read_b128 v[152:155], v97
	ds_read_b128 v[160:163], v102 offset:0
	ds_read_b128 v[168:171], v102 offset:2048
	ds_read_b128 v[156:159], v97 offset:512
	ds_read_b128 v[164:167], v102 offset:512
	ds_read_b128 v[172:175], v102 offset:2560
	s_add_i32 m0, s76, 0
	s_nop 0
	global_load_lds_dwordx4 v[110:111], off
	v_lshl_add_u64 v[110:111], v[110:111], 0, s[78:79]
	s_add_i32 m0, s77, 0
	s_nop 0
	global_load_lds_dwordx4 v[112:113], off
	v_lshl_add_u64 v[112:113], v[112:113], 0, s[78:79]
	s_add_i32 m0, s77, 1024
	s_nop 0
	global_load_lds_dwordx4 v[114:115], off
	v_lshl_add_u64 v[114:115], v[114:115], 0, s[78:79]
	s_waitcnt lgkmcnt(3)
	v_mfma_f32_16x16x32_bf16 v[120:123], v[152:155], v[160:163], v[120:123]
	v_mfma_f32_16x16x32_bf16 v[124:127], v[152:155], v[168:171], v[124:127]
	s_waitcnt lgkmcnt(0)
	v_mfma_f32_16x16x32_bf16 v[120:123], v[156:159], v[164:167], v[120:123]
	v_mfma_f32_16x16x32_bf16 v[124:127], v[156:159], v[172:175], v[124:127]
	s_waitcnt vmcnt(9)
	s_barrier
	ds_read_b128 v[128:131], v98
	ds_read_b128 v[136:139], v103 offset:0
	ds_read_b128 v[144:147], v103 offset:2048
	ds_read_b128 v[132:135], v98 offset:512
	ds_read_b128 v[140:143], v103 offset:512
	ds_read_b128 v[148:151], v103 offset:2560
	s_add_i32 m0, s76, 24576
	s_nop 0
	global_load_lds_dwordx4 v[110:111], off
	v_lshl_add_u64 v[110:111], v[110:111], 0, s[78:79]
	s_add_i32 m0, s77, 24576
	s_nop 0
	global_load_lds_dwordx4 v[112:113], off
	v_lshl_add_u64 v[112:113], v[112:113], 0, s[78:79]
	s_add_i32 m0, s77, 25600
	s_nop 0
	global_load_lds_dwordx4 v[114:115], off
	v_lshl_add_u64 v[114:115], v[114:115], 0, s[78:79]
	s_waitcnt lgkmcnt(3)
	v_mfma_f32_16x16x32_bf16 v[120:123], v[128:131], v[136:139], v[120:123]
	v_mfma_f32_16x16x32_bf16 v[124:127], v[128:131], v[144:147], v[124:127]
	s_waitcnt lgkmcnt(0)
	v_mfma_f32_16x16x32_bf16 v[120:123], v[132:135], v[140:143], v[120:123]
	v_mfma_f32_16x16x32_bf16 v[124:127], v[132:135], v[148:151], v[124:127]
	s_waitcnt vmcnt(9)
	s_barrier
; template <class F>
; __device__ __forceinline__ void small_gemm_ks(LAS unsigned char* lds, const bf16_t* A, int lda, const bf16_t* Bt, int ldb, int K, int N, int a_grp_cols, int bx, int G, int tid, const F& f) {
;     ...
;         for (int k0 = 0; k0 < KH; k0 += 32) { const bf16x8 av = *(const bf16x8*)(ap + k0);
; #pragma unroll
;             for (int nt = 0; nt < 2; ++nt) { const bf16x8 bv = *(const bf16x8*)(bp + (size_t)nt * 16 * ldb + k0); acc[nt] = __builtin_amdgcn_mfma_f32_16x16x32_bf16(av, bv, acc[nt], 0, 0, 0); } }
	ds_read_b128 v[152:155], v99
	ds_read_b128 v[160:163], v104 offset:0
	ds_read_b128 v[168:171], v104 offset:2048
	ds_read_b128 v[156:159], v99 offset:512
	ds_read_b128 v[164:167], v104 offset:512
	ds_read_b128 v[172:175], v104 offset:2560
	s_add_i32 m0, s76, 49152
	s_nop 0
	global_load_lds_dwordx4 v[110:111], off
	v_lshl_add_u64 v[110:111], v[110:111], 0, s[78:79]
	s_add_i32 m0, s77, 49152
	s_nop 0
	global_load_lds_dwordx4 v[112:113], off
	v_lshl_add_u64 v[112:113], v[112:113], 0, s[78:79]
	s_add_i32 m0, s77, 50176
	s_nop 0
	global_load_lds_dwordx4 v[114:115], off
	v_lshl_add_u64 v[114:115], v[114:115], 0, s[78:79]
	s_waitcnt lgkmcnt(3)
	v_mfma_f32_16x16x32_bf16 v[120:123], v[152:155], v[160:163], v[120:123]
	v_mfma_f32_16x16x32_bf16 v[124:127], v[152:155], v[168:171], v[124:127]
	s_waitcnt lgkmcnt(0)
	v_mfma_f32_16x16x32_bf16 v[120:123], v[156:159], v[164:167], v[120:123]
	v_mfma_f32_16x16x32_bf16 v[124:127], v[156:159], v[172:175], v[124:127]
	s_waitcnt vmcnt(9)
	s_barrier
	ds_read_b128 v[128:131], v100
	ds_read_b128 v[136:139], v105 offset:0
	ds_read_b128 v[144:147], v105 offset:2048
	ds_read_b128 v[132:135], v100 offset:512
	ds_read_b128 v[140:143], v105 offset:512
	ds_read_b128 v[148:151], v105 offset:2560
	s_add_i32 m0, s76, 73728
	s_nop 0
	global_load_lds_dwordx4 v[110:111], off
	v_lshl_add_u64 v[110:111], v[110:111], 0, s[78:79]
	s_add_i32 m0, s77, 73728
	s_nop 0
	global_load_lds_dwordx4 v[112:113], off
	v_lshl_add_u64 v[112:113], v[112:113], 0, s[78:79]
	s_add_i32 m0, s77, 74752
	s_nop 0
	global_load_lds_dwordx4 v[114:115], off
	v_lshl_add_u64 v[114:115], v[114:115], 0, s[78:79]
	s_waitcnt lgkmcnt(3)
	v_mfma_f32_16x16x32_bf16 v[120:123], v[128:131], v[136:139], v[120:123]
	v_mfma_f32_16x16x32_bf16 v[124:127], v[128:131], v[144:147], v[124:127]
	s_waitcnt lgkmcnt(0)
	v_mfma_f32_16x16x32_bf16 v[120:123], v[132:135], v[140:143], v[120:123]
	v_mfma_f32_16x16x32_bf16 v[124:127], v[132:135], v[148:151], v[124:127]
	s_waitcnt vmcnt(9)
	s_barrier
	ds_read_b128 v[152:155], v96
	ds_read_b128 v[160:163], v101 offset:0
	ds_read_b128 v[168:171], v101 offset:2048
	ds_read_b128 v[156:159], v96 offset:512
	ds_read_b128 v[164:167], v101 offset:512
	ds_read_b128 v[172:175], v101 offset:2560
	s_add_i32 m0, s76, 98304
	s_nop 0
	global_load_lds_dwordx4 v[110:111], off
	v_lshl_add_u64 v[110:111], v[110:111], 0, s[78:79]
	s_add_i32 m0, s77, 98304
	s_nop 0
	global_load_lds_dwordx4 v[112:113], off
	v_lshl_add_u64 v[112:113], v[112:113], 0, s[78:79]
	s_add_i32 m0, s77, 99328
	s_nop 0
	global_load_lds_dwordx4 v[114:115], off
	v_lshl_add_u64 v[114:115], v[114:115], 0, s[78:79]
	s_waitcnt lgkmcnt(3)
	v_mfma_f32_16x16x32_bf16 v[120:123], v[152:155], v[160:163], v[120:123]
	v_mfma_f32_16x16x32_bf16 v[124:127], v[152:155], v[168:171], v[124:127]
	s_waitcnt lgkmcnt(0)
	v_mfma_f32_16x16x32_bf16 v[120:123], v[156:159], v[164:167], v[120:123]
	v_mfma_f32_16x16x32_bf16 v[124:127], v[156:159], v[172:175], v[124:127]
	s_waitcnt vmcnt(9)
	s_barrier
	ds_read_b128 v[128:131], v97
	ds_read_b128 v[136:139], v102 offset:0
	ds_read_b128 v[144:147], v102 offset:2048
	ds_read_b128 v[132:135], v97 offset:512
	ds_read_b128 v[140:143], v102 offset:512
	ds_read_b128 v[148:151], v102 offset:2560
	s_add_i32 m0, s76, 0
	s_nop 0
	global_load_lds_dwordx4 v[110:111], off
	v_lshl_add_u64 v[110:111], v[110:111], 0, s[78:79]
	s_add_i32 m0, s77, 0
	s_nop 0
	global_load_lds_dwordx4 v[112:113], off
	v_lshl_add_u64 v[112:113], v[112:113], 0, s[78:79]
	s_add_i32 m0, s77, 1024
	s_nop 0
	global_load_lds_dwordx4 v[114:115], off
	v_lshl_add_u64 v[114:115], v[114:115], 0, s[78:79]
	s_waitcnt lgkmcnt(3)
	v_mfma_f32_16x16x32_bf16 v[120:123], v[128:131], v[136:139], v[120:123]
	v_mfma_f32_16x16x32_bf16 v[124:127], v[128:131], v[144:147], v[124:127]
	s_waitcnt lgkmcnt(0)
	v_mfma_f32_16x16x32_bf16 v[120:123], v[132:135], v[140:143], v[120:123]
	v_mfma_f32_16x16x32_bf16 v[124:127], v[132:135], v[148:151], v[124:127]
	s_waitcnt vmcnt(9)
	s_barrier
; #define LAS __attribute__((address_space(3)))
; #define LDS_SYNC() do { asm volatile("s_waitcnt lgkmcnt(0)" ::: "memory"); __builtin_amdgcn_s_barrier(); asm volatile("" ::: "memory"); } while (0)
; template <class F>
; __device__ __forceinline__ void small_gemm_ks(LAS unsigned char* lds, const bf16_t* A, int lda, const bf16_t* Bt, int ldb, int K, int N, int a_grp_cols, int bx, int G, int tid, const F& f) {
;     ...
;         for (int k0 = 0; k0 < KH; k0 += 32) { const bf16x8 av = *(const bf16x8*)(ap + k0);
; #pragma unroll
;             for (int nt = 0; nt < 2; ++nt) { const bf16x8 bv = *(const bf16x8*)(bp + (size_t)nt * 16 * ldb + k0); acc[nt] = __builtin_amdgcn_mfma_f32_16x16x32_bf16(av, bv, acc[nt], 0, 0, 0); } }
;         if (kh == 1) { *(LAS f32x4*)(lds + ((wq * 2 + 0) * 64 + lane) * 16) = acc[0]; *(LAS f32x4*)(lds + ((wq * 2 + 1) * 64 + lane) * 16) = acc[1]; }
;         LDS_SYNC();
	ds_read_b128 v[152:155], v98
	ds_read_b128 v[160:163], v103 offset:0
	ds_read_b128 v[168:171], v103 offset:2048
	ds_read_b128 v[156:159], v98 offset:512
	ds_read_b128 v[164:167], v103 offset:512
	ds_read_b128 v[172:175], v103 offset:2560
	s_add_i32 m0, s76, 24576
	s_nop 0
	global_load_lds_dwordx4 v[110:111], off
	v_lshl_add_u64 v[110:111], v[110:111], 0, s[78:79]
	s_add_i32 m0, s77, 24576
	s_nop 0
	global_load_lds_dwordx4 v[112:113], off
	v_lshl_add_u64 v[112:113], v[112:113], 0, s[78:79]
	s_add_i32 m0, s77, 25600
	s_nop 0
	global_load_lds_dwordx4 v[114:115], off
	v_lshl_add_u64 v[114:115], v[114:115], 0, s[78:79]
	s_waitcnt lgkmcnt(3)
	v_mfma_f32_16x16x32_bf16 v[120:123], v[152:155], v[160:163], v[120:123]
	v_mfma_f32_16x16x32_bf16 v[124:127], v[152:155], v[168:171], v[124:127]
	s_waitcnt lgkmcnt(0)
	v_mfma_f32_16x16x32_bf16 v[120:123], v[156:159], v[164:167], v[120:123]
	v_mfma_f32_16x16x32_bf16 v[124:127], v[156:159], v[172:175], v[124:127]
	s_waitcnt vmcnt(9)
	s_barrier
	ds_read_b128 v[128:131], v99
	ds_read_b128 v[136:139], v104 offset:0
	ds_read_b128 v[144:147], v104 offset:2048
	ds_read_b128 v[132:135], v99 offset:512
	ds_read_b128 v[140:143], v104 offset:512
	ds_read_b128 v[148:151], v104 offset:2560
	s_waitcnt lgkmcnt(3)
	v_mfma_f32_16x16x32_bf16 v[120:123], v[128:131], v[136:139], v[120:123]
	v_mfma_f32_16x16x32_bf16 v[124:127], v[128:131], v[144:147], v[124:127]
	s_waitcnt lgkmcnt(0)
	v_mfma_f32_16x16x32_bf16 v[120:123], v[132:135], v[140:143], v[120:123]
	v_mfma_f32_16x16x32_bf16 v[124:127], v[132:135], v[148:151], v[124:127]
	s_waitcnt vmcnt(6)
	s_barrier
	ds_read_b128 v[152:155], v100
	ds_read_b128 v[160:163], v105 offset:0
	ds_read_b128 v[168:171], v105 offset:2048
	ds_read_b128 v[156:159], v100 offset:512
	ds_read_b128 v[164:167], v105 offset:512
	ds_read_b128 v[172:175], v105 offset:2560
	s_waitcnt lgkmcnt(3)
	v_mfma_f32_16x16x32_bf16 v[120:123], v[152:155], v[160:163], v[120:123]
	v_mfma_f32_16x16x32_bf16 v[124:127], v[152:155], v[168:171], v[124:127]
	s_waitcnt lgkmcnt(0)
	v_mfma_f32_16x16x32_bf16 v[120:123], v[156:159], v[164:167], v[120:123]
	v_mfma_f32_16x16x32_bf16 v[124:127], v[156:159], v[172:175], v[124:127]
	s_waitcnt vmcnt(3)
	s_barrier
	ds_read_b128 v[128:131], v96
	ds_read_b128 v[136:139], v101 offset:0
	ds_read_b128 v[144:147], v101 offset:2048
	ds_read_b128 v[132:135], v96 offset:512
	ds_read_b128 v[140:143], v101 offset:512
	ds_read_b128 v[148:151], v101 offset:2560
	s_waitcnt lgkmcnt(3)
	v_mfma_f32_16x16x32_bf16 v[120:123], v[128:131], v[136:139], v[120:123]
	v_mfma_f32_16x16x32_bf16 v[124:127], v[128:131], v[144:147], v[124:127]
	s_waitcnt lgkmcnt(0)
	v_mfma_f32_16x16x32_bf16 v[120:123], v[132:135], v[140:143], v[120:123]
	v_mfma_f32_16x16x32_bf16 v[124:127], v[132:135], v[148:151], v[124:127]
	s_waitcnt vmcnt(0)
	s_barrier
	ds_read_b128 v[152:155], v97
	ds_read_b128 v[160:163], v102 offset:0
	ds_read_b128 v[168:171], v102 offset:2048
	ds_read_b128 v[156:159], v97 offset:512
	ds_read_b128 v[164:167], v102 offset:512
	ds_read_b128 v[172:175], v102 offset:2560
	s_waitcnt lgkmcnt(3)
	v_mfma_f32_16x16x32_bf16 v[120:123], v[152:155], v[160:163], v[120:123]
	v_mfma_f32_16x16x32_bf16 v[124:127], v[152:155], v[168:171], v[124:127]
	s_waitcnt lgkmcnt(0)
	v_mfma_f32_16x16x32_bf16 v[120:123], v[156:159], v[164:167], v[120:123]
	v_mfma_f32_16x16x32_bf16 v[124:127], v[156:159], v[172:175], v[124:127]
	s_barrier
	s_lshl_b32 s59, s82, 11
	s_lshl_b32 s62, s83, 1
	s_add_i32 s59, s59, s62
	s_add_u32 s60, s54, s59
	s_addc_u32 s61, s55, 0
	s_add_u32 s60, s60, 0x5700000
	s_addc_u32 s61, s61, 0
	v_lshl_add_u64 v[176:177], s[60:61], 0, v[106:107]
	s_mov_b32 s62, 0x1000
	s_mov_b32 s63, 0
	v_lshl_add_u64 v[178:179], v[176:177], 0, s[62:63]
	s_cmp_eq_u32 s70, 0
	s_cbranch_scc1 .Lsg_dn1_lo
	s_nop 4
	ds_write_b128 v109, v[120:123]
	ds_write_b128 v109, v[124:127] offset:1024
	s_waitcnt lgkmcnt(0)
	s_barrier
	s_branch .Lsg_dn1_done
